# P4 stats exchange: dropped the L1 invalidate after the partner wait (slots are read with device-scope loads)
# speedup vs baseline: 1.0139x; 1.0021x over previous
.LBB0_695:
	s_andn2_b64 vcc, exec, s[38:39]
	s_cbranch_vccz .LBB0_701
	s_waitcnt lgkmcnt(0)
	s_and_saveexec_b64 s[18:19], s[4:5]
	s_xor_b64 s[4:5], exec, s[18:19]
	s_cbranch_execz .LBB0_698
.LBB0_698:
	s_or_saveexec_b64 s[18:19], s[4:5]
	s_mov_b64 s[4:5], 0
	s_xor_b64 exec, exec, s[18:19]
	s_cbranch_execz .LBB0_700
	s_and_b32 s16, s16, 0xff
	s_or_b32 s16, s16, 0x700
	v_mov_b32_e32 v164, s16
	global_atomic_cmpswap v165, v[164:165], s[24:25] offset:4
	s_mov_b64 s[4:5], exec
	global_store_dword v165, v187, s[24:25] sc1

.LBB0_702:
	s_waitcnt vmcnt(0)
	s_and_b64 exec, exec, s[6:7]
	v_cndmask_b32_e64 v130, 0, 1, s[16:17]
	ds_write_b32 v165, v130 offset:10240
